# attention: local V^T window of the workgroup's 8 waves (9 image rows x 64 d) staged once per round in LDS by full-line DMA pieces (XOR-swizzled), context buffers single-buffered
# speedup vs baseline: 1.5418x; 1.0031x over previous
.LBB0_479:
	s_andn2_b64 vcc, exec, s[0:1]
	s_cbranch_vccnz .LBB0_609
	s_sub_i32 s86, s12, s13
	s_and_b32 s0, s86, 3
	s_bfe_u32 s1, s86, 0x10002
	s_bfe_u32 s6, s86, 0x20003
	s_bfe_u32 s7, s86, 0x50005
	s_lshr_b32 s8, s86, 10
	s_lshl_b32 s7, s7, 1
	s_or_b32 s1, s1, s7
	s_sub_i32 s7, s1, 4
	s_max_i32 s7, s7, 0
	s_min_i32 s7, s7, 56
	s_lshl_b32 s9, s0, 4
	s_sub_i32 s9, s9, 8
	s_max_i32 s9, s9, 0
	s_min_i32 s9, s9, 32
	v_and_b32_e32 v206, 15, v205
	v_lshrrev_b32_e32 v207, 4, v205
	s_mul_i32 s10, s6, 15
	s_add_i32 s10, s10, s7
	s_sub_i32 s10, s10, s1
	s_add_i32 s10, s10, 7
	s_mul_i32 s10, s10, 31
	s_add_i32 s10, s10, s9
	s_lshl_b32 s11, s0, 4
	s_sub_i32 s10, s10, s11
	s_add_i32 s10, s10, 15
	v_lshlrev_b32_e32 v214, 3, v207
	v_sub_u32_e32 v214, v214, v206
	v_add_u32_e32 v214, s10, v214
	v_ashrrev_i32_e32 v215, 31, v214
	v_lshl_add_u64 v[212:213], v[214:215], 2, s[56:57]
	global_load_dwordx4 v[0:3], v[212:213], off offset:0
	global_load_dwordx4 v[4:7], v[212:213], off offset:16
	global_load_dwordx4 v[8:11], v[212:213], off offset:124
	global_load_dwordx4 v[12:15], v[212:213], off offset:140
	global_load_dwordx4 v[16:19], v[212:213], off offset:248
	global_load_dwordx4 v[20:23], v[212:213], off offset:264
	global_load_dwordx4 v[24:27], v[212:213], off offset:372
	global_load_dwordx4 v[28:31], v[212:213], off offset:388
	s_lshl_b32 s10, s8, 12
	s_lshl_b32 s11, s1, 6
	s_add_i32 s10, s10, s11
	s_lshl_b32 s11, s0, 4
	s_add_i32 s10, s10, s11
	s_addk_i32 s10, 0x400
	s_mul_i32 s11, s10, 0xe00
	s_lshl_b32 s16, s6, 7
	s_add_u32 s16, s16, 0x5e00000
	s_add_u32 s18, s4, s16
	s_addc_u32 s19, s5, 0
	s_add_u32 s20, s18, s11
	s_addc_u32 s21, s19, 0
	v_mul_u32_u24_e32 v208, 0xe00, v206
	v_lshl_add_u32 v208, v207, 4, v208
	global_load_dwordx4 v[128:131], v208, s[20:21] offset:1536
	global_load_dwordx4 v[132:135], v208, s[20:21] offset:1600
	v_lshrrev_b32_e32 v209, 2, v206
	v_and_b32_e32 v210, 3, v206
	v_lshl_add_u32 v209, v209, 3, v210
	v_mul_u32_u24_e32 v209, 0xe00, v209
	v_lshl_add_u32 v209, v207, 4, v209
	s_lshl_b32 s10, s8, 12
	s_lshl_b32 s11, s7, 6
	s_add_i32 s10, s10, s11
	s_add_i32 s10, s10, s9
	s_addk_i32 s10, 0x400
	s_mul_i32 s10, s10, 0xe00
	s_add_u32 s22, s18, s10
	s_addc_u32 s23, s19, 0
	s_lshl_b32 s10, s8, 8
	s_mul_i32 s10, s10, 0xe00
	s_add_u32 s24, s18, s10
	s_addc_u32 s25, s19, 0
	s_mov_b32 s38, 0
	s_barrier
	v_lshrrev_b32_e32 v214, 6, v186
	v_lshlrev_b32_e32 v211, 4, v205
	v_add_u32_e32 v211, s38, v211
	v_readfirstlane_b32 s11, v214
	s_lshl_b32 s10, s8, 8
	s_lshl_b32 s26, s6, 6
	s_add_i32 s10, s10, s26
	s_lshl_b32 s10, s10, 9
	s_add_u32 s10, s10, 0xa200000
	s_add_u32 s26, s4, s10
	s_addc_u32 s27, s5, 0
	v_mov_b32_e32 v136, v209
	s_add_i32 s10, s11, 0
	s_lshr_b32 s36, s10, 2
	s_lshl_b32 s36, s36, 5
	s_bfe_u32 s37, s10, 0x10001
	s_lshl_b32 s37, s37, 2
	s_add_i32 s36, s36, s37
	s_mul_i32 s36, s36, 0xe00
	s_and_b32 s37, s10, 1
	s_lshl_b32 s37, s37, 6
	s_add_i32 s36, s36, s37
	s_addk_i32 s36, 0x800
	s_add_u32 s36, s24, s36
	s_addc_u32 s37, s25, 0
	v_lshl_add_u64 v[214:215], s[36:37], 0, v[136:137]
	s_lshl_b32 s10, s10, 10
	s_add_i32 m0, s10, s38
	s_nop 0
	global_load_lds_dwordx4 v[214:215], off
	s_add_i32 s10, s11, 8
	s_lshr_b32 s36, s10, 2
	s_lshl_b32 s36, s36, 5
	s_bfe_u32 s37, s10, 0x10001
	s_lshl_b32 s37, s37, 2
	s_add_i32 s36, s36, s37
	s_mul_i32 s36, s36, 0xe00
	s_and_b32 s37, s10, 1
	s_lshl_b32 s37, s37, 6
	s_add_i32 s36, s36, s37
	s_addk_i32 s36, 0x800
	s_add_u32 s36, s24, s36
	s_addc_u32 s37, s25, 0
	v_lshl_add_u64 v[214:215], s[36:37], 0, v[136:137]
	s_lshl_b32 s10, s10, 10
	s_add_i32 m0, s10, s38
	s_nop 0
	global_load_lds_dwordx4 v[214:215], off
	s_add_i32 s10, s11, 16
	s_lshr_b32 s36, s10, 2
	s_lshl_b32 s36, s36, 5
	s_bfe_u32 s37, s10, 0x10001
	s_lshl_b32 s37, s37, 2
	s_add_i32 s36, s36, s37
	s_mul_i32 s36, s36, 0xe00
	s_and_b32 s37, s10, 1
	s_lshl_b32 s37, s37, 6
	s_add_i32 s36, s36, s37
	s_addk_i32 s36, 0x800
	s_add_u32 s36, s24, s36
	s_addc_u32 s37, s25, 0
	v_lshl_add_u64 v[214:215], s[36:37], 0, v[136:137]
	s_lshl_b32 s10, s10, 10
	s_add_i32 m0, s10, s38
	s_nop 0
	global_load_lds_dwordx4 v[214:215], off
	s_add_i32 s10, s11, 24
	s_lshr_b32 s36, s10, 2
	s_lshl_b32 s36, s36, 5
	s_bfe_u32 s37, s10, 0x10001
	s_lshl_b32 s37, s37, 2
	s_add_i32 s36, s36, s37
	s_mul_i32 s36, s36, 0xe00
	s_and_b32 s37, s10, 1
	s_lshl_b32 s37, s37, 6
	s_add_i32 s36, s36, s37
	s_addk_i32 s36, 0x800
	s_add_u32 s36, s24, s36
	s_addc_u32 s37, s25, 0
	v_lshl_add_u64 v[214:215], s[36:37], 0, v[136:137]
	s_lshl_b32 s10, s10, 10
	s_add_i32 m0, s10, s38
	s_nop 0
	global_load_lds_dwordx4 v[214:215], off
	v_lshlrev_b32_e32 v136, 9, v206
	v_lshl_add_u32 v136, v207, 4, v136
	s_add_i32 s10, s11, 0
	s_and_b32 s36, s10, 3
	s_lshl_b32 s36, s36, 13
	s_lshr_b32 s37, s10, 2
	s_lshl_b32 s37, s37, 6
	s_add_i32 s36, s36, s37
	s_add_u32 s36, s26, s36
	s_addc_u32 s37, s27, 0
	v_lshl_add_u64 v[214:215], s[36:37], 0, v[136:137]
	s_lshl_b32 s10, s10, 10
	s_add_i32 s10, s10, s38
	s_add_i32 m0, s10, 0x8000
	s_nop 0
	global_load_lds_dwordx4 v[214:215], off
	s_add_i32 s10, s11, 8
	s_and_b32 s36, s10, 3
	s_lshl_b32 s36, s36, 13
	s_lshr_b32 s37, s10, 2
	s_lshl_b32 s37, s37, 6
	s_add_i32 s36, s36, s37
	s_add_u32 s36, s26, s36
	s_addc_u32 s37, s27, 0
	v_lshl_add_u64 v[214:215], s[36:37], 0, v[136:137]
	s_lshl_b32 s10, s10, 10
	s_add_i32 s10, s10, s38
	s_add_i32 m0, s10, 0x8000
	s_nop 0
	global_load_lds_dwordx4 v[214:215], off
	s_add_i32 s10, s11, 16
	s_and_b32 s36, s10, 3
	s_lshl_b32 s36, s36, 13
	s_lshr_b32 s37, s10, 2
	s_lshl_b32 s37, s37, 6
	s_add_i32 s36, s36, s37
	s_add_u32 s36, s26, s36
	s_addc_u32 s37, s27, 0
	v_lshl_add_u64 v[214:215], s[36:37], 0, v[136:137]
	s_lshl_b32 s10, s10, 10
	s_add_i32 s10, s10, s38
	s_add_i32 m0, s10, 0x8000
	s_nop 0
	global_load_lds_dwordx4 v[214:215], off
	s_add_i32 s10, s11, 24
	s_and_b32 s36, s10, 3
	s_lshl_b32 s36, s36, 13
	s_lshr_b32 s37, s10, 2
	s_lshl_b32 s37, s37, 6
	s_add_i32 s36, s36, s37
	s_add_u32 s36, s26, s36
	s_addc_u32 s37, s27, 0
	v_lshl_add_u64 v[214:215], s[36:37], 0, v[136:137]
	s_lshl_b32 s10, s10, 10
	s_add_i32 s10, s10, s38
	s_add_i32 m0, s10, 0x8000
	s_nop 0
	global_load_lds_dwordx4 v[214:215], off
	s_bfe_u32 s10, s86, 0x50005
	s_lshl_b32 s10, s10, 1
	s_sub_i32 s10, s10, 4
	s_max_i32 s10, s10, 0
	s_min_i32 s10, s10, 56
	s_lshl_b32 s37, s8, 8
	s_lshl_b32 s26, s6, 6
	s_add_i32 s37, s37, s26
	s_lshl_b32 s26, s11, 3
	s_add_i32 s37, s37, s26
	s_lshl_b32 s37, s37, 13
	s_lshl_b32 s26, s10, 7
	s_add_i32 s37, s37, s26
	s_add_u32 s37, s37, 0x9a00000
	s_add_u32 s26, s4, s37
	s_addc_u32 s27, s5, 0
	v_lshrrev_b32_e32 v136, 3, v205
	v_lshrrev_b32_e32 v214, 4, v205
	s_and_b32 s37, s11, 1
	s_lshl_b32 s37, s37, 2
	v_add_u32_e32 v214, s37, v214
	v_and_b32_e32 v214, 7, v214
	v_and_b32_e32 v215, 7, v205
	v_xor_b32_e32 v214, v214, v215
	v_lshlrev_b32_e32 v214, 4, v214
	v_lshl_add_u32 v136, v136, 13, v214
	s_lshl_b32 s37, s11, 10
	s_add_i32 s37, s37, 0x10000
	v_lshl_add_u64 v[214:215], s[26:27], 0, v[136:137]
	s_add_i32 m0, s37, 0x0
	s_nop 0
	global_load_lds_dwordx4 v[214:215], off
	s_add_u32 s26, s26, 0x80
	s_addc_u32 s27, s27, 0
	v_lshl_add_u64 v[214:215], s[26:27], 0, v[136:137]
	s_add_i32 m0, s37, 0x2000
	s_nop 0
	global_load_lds_dwordx4 v[214:215], off
	s_add_u32 s26, s26, 0x80
	s_addc_u32 s27, s27, 0
	v_lshl_add_u64 v[214:215], s[26:27], 0, v[136:137]
	s_add_i32 m0, s37, 0x4000
	s_nop 0
	global_load_lds_dwordx4 v[214:215], off
	s_add_u32 s26, s26, 0x80
	s_addc_u32 s27, s27, 0
	v_lshl_add_u64 v[214:215], s[26:27], 0, v[136:137]
	s_add_i32 m0, s37, 0x6000
	s_nop 0
	global_load_lds_dwordx4 v[214:215], off
	s_add_u32 s26, s26, 0x80
	s_addc_u32 s27, s27, 0
	v_lshl_add_u64 v[214:215], s[26:27], 0, v[136:137]
	s_add_i32 m0, s37, 0x8000
	s_nop 0
	global_load_lds_dwordx4 v[214:215], off
	s_add_u32 s26, s26, 0x80
	s_addc_u32 s27, s27, 0
	v_lshl_add_u64 v[214:215], s[26:27], 0, v[136:137]
	s_add_i32 m0, s37, 0xa000
	s_nop 0
	global_load_lds_dwordx4 v[214:215], off
	s_add_u32 s26, s26, 0x80
	s_addc_u32 s27, s27, 0
	v_lshl_add_u64 v[214:215], s[26:27], 0, v[136:137]
	s_add_i32 m0, s37, 0xc000
	s_nop 0
	global_load_lds_dwordx4 v[214:215], off
	s_add_u32 s26, s26, 0x80
	s_addc_u32 s27, s27, 0
	v_lshl_add_u64 v[214:215], s[26:27], 0, v[136:137]
	s_add_i32 m0, s37, 0xe000
	s_nop 0
	global_load_lds_dwordx4 v[214:215], off
	s_add_u32 s26, s26, 0x80
	s_addc_u32 s27, s27, 0
	v_lshl_add_u64 v[214:215], s[26:27], 0, v[136:137]
	s_add_i32 m0, s37, 0x10000
	s_nop 0
	global_load_lds_dwordx4 v[214:215], off
	global_load_dwordx4 v[138:141], v209, s[22:23] offset:2048
	global_load_dwordx4 v[142:145], v209, s[22:23] offset:2112
	s_add_u32 s22, s22, 0x3800
	s_addc_u32 s23, s23, 0
	global_load_dwordx4 v[146:149], v209, s[22:23] offset:2048
	global_load_dwordx4 v[150:153], v209, s[22:23] offset:2112
	s_add_u32 s22, s22, 0x34800
	s_addc_u32 s23, s23, 0
	global_load_dwordx4 v[154:157], v209, s[22:23] offset:2048
	global_load_dwordx4 v[158:161], v209, s[22:23] offset:2112
	s_add_u32 s22, s22, 0x3800
	s_addc_u32 s23, s23, 0
	global_load_dwordx4 v[162:165], v209, s[22:23] offset:2048
	global_load_dwordx4 v[166:169], v209, s[22:23] offset:2112
	s_add_u32 s22, s22, 0x34800
	s_addc_u32 s23, s23, 0
	global_load_dwordx4 v[170:173], v209, s[22:23] offset:2048
	global_load_dwordx4 v[174:177], v209, s[22:23] offset:2112
	s_add_u32 s22, s22, 0x3800
	s_addc_u32 s23, s23, 0
	global_load_dwordx4 v[178:181], v209, s[22:23] offset:2048
	global_load_dwordx4 v[182:185], v209, s[22:23] offset:2112
	s_add_u32 s22, s22, 0x34800
	s_addc_u32 s23, s23, 0
	s_lshl_b32 s10, s0, 4
	s_sub_i32 s10, s10, 8
	v_add_u32_e32 v210, s10, v206
	v_med3_i32 v210, v210, 0, 48
	v_lshl_add_u32 v214, v207, 3, s9
	v_sub_u32_e32 v210, v214, v210
	v_writelane_b32 v136, s0, 0
	v_writelane_b32 v136, s1, 1
	v_writelane_b32 v136, s6, 2
	v_writelane_b32 v136, s7, 3
	v_writelane_b32 v136, s8, 4
	v_writelane_b32 v136, s9, 5
	v_add_u32_e32 v214, 0, v210
	v_cmp_gt_u32_e64 s[26:27], 16, v214
	v_add_u32_e32 v214, 1, v210
	v_cmp_gt_u32_e64 s[36:37], 16, v214
	v_add_u32_e32 v214, 2, v210
	v_cmp_gt_u32_e64 s[10:11], 16, v214
	v_add_u32_e32 v214, 3, v210
	v_cmp_gt_u32_e64 s[0:1], 16, v214
	v_add_u32_e32 v214, 4, v210
	v_cmp_gt_u32_e64 s[6:7], 16, v214
	v_add_u32_e32 v214, 5, v210
	v_cmp_gt_u32_e64 s[8:9], 16, v214
	v_add_u32_e32 v214, 6, v210
	v_cmp_gt_u32_e64 s[16:17], 16, v214
	v_add_u32_e32 v214, 7, v210
	v_cmp_gt_u32_e64 s[20:21], 16, v214
	v_mov_b32_e32 v216, 0xf2c9f2ca
	s_waitcnt vmcnt(31)
	v_mul_f32_e32 v0, 0x41000000, v0
	v_mul_f32_e32 v1, 0x41000000, v1
	v_mul_f32_e32 v2, 0x41000000, v2
	v_mul_f32_e32 v3, 0x41000000, v3
	v_mul_f32_e32 v4, 0x41000000, v4
	v_mul_f32_e32 v5, 0x41000000, v5
	v_mul_f32_e32 v6, 0x41000000, v6
	v_mul_f32_e32 v7, 0x41000000, v7
	v_cndmask_b32_e64 v0, v216, v0, s[26:27]
	v_cndmask_b32_e64 v1, v216, v1, s[36:37]
	v_cndmask_b32_e64 v2, v216, v2, s[10:11]
	v_cndmask_b32_e64 v3, v216, v3, s[0:1]
	v_cndmask_b32_e64 v4, v216, v4, s[6:7]
	v_cndmask_b32_e64 v5, v216, v5, s[8:9]
	v_cndmask_b32_e64 v6, v216, v6, s[16:17]
	v_cndmask_b32_e64 v7, v216, v7, s[20:21]
	v_mul_f32_e32 v8, 0x41000000, v8
	v_mul_f32_e32 v9, 0x41000000, v9
	v_mul_f32_e32 v10, 0x41000000, v10
	v_mul_f32_e32 v11, 0x41000000, v11
	v_mul_f32_e32 v12, 0x41000000, v12
	v_mul_f32_e32 v13, 0x41000000, v13
	v_mul_f32_e32 v14, 0x41000000, v14
	v_mul_f32_e32 v15, 0x41000000, v15
	v_cndmask_b32_e64 v8, v216, v8, s[26:27]
	v_cndmask_b32_e64 v9, v216, v9, s[36:37]
	v_cndmask_b32_e64 v10, v216, v10, s[10:11]
	v_cndmask_b32_e64 v11, v216, v11, s[0:1]
	v_cndmask_b32_e64 v12, v216, v12, s[6:7]
	v_cndmask_b32_e64 v13, v216, v13, s[8:9]
	v_cndmask_b32_e64 v14, v216, v14, s[16:17]
	v_cndmask_b32_e64 v15, v216, v15, s[20:21]
	v_mul_f32_e32 v16, 0x41000000, v16
	v_mul_f32_e32 v17, 0x41000000, v17
	v_mul_f32_e32 v18, 0x41000000, v18
	v_mul_f32_e32 v19, 0x41000000, v19
	v_mul_f32_e32 v20, 0x41000000, v20
	v_mul_f32_e32 v21, 0x41000000, v21
	v_mul_f32_e32 v22, 0x41000000, v22
	v_mul_f32_e32 v23, 0x41000000, v23
	v_cndmask_b32_e64 v16, v216, v16, s[26:27]
	v_cndmask_b32_e64 v17, v216, v17, s[36:37]
	v_cndmask_b32_e64 v18, v216, v18, s[10:11]
	v_cndmask_b32_e64 v19, v216, v19, s[0:1]
	v_cndmask_b32_e64 v20, v216, v20, s[6:7]
	v_cndmask_b32_e64 v21, v216, v21, s[8:9]
	v_cndmask_b32_e64 v22, v216, v22, s[16:17]
	v_cndmask_b32_e64 v23, v216, v23, s[20:21]
	v_mul_f32_e32 v24, 0x41000000, v24
	v_mul_f32_e32 v25, 0x41000000, v25
	v_mul_f32_e32 v26, 0x41000000, v26
	v_mul_f32_e32 v27, 0x41000000, v27
	v_mul_f32_e32 v28, 0x41000000, v28
	v_mul_f32_e32 v29, 0x41000000, v29
	v_mul_f32_e32 v30, 0x41000000, v30
	v_mul_f32_e32 v31, 0x41000000, v31
	v_cndmask_b32_e64 v24, v216, v24, s[26:27]
	v_cndmask_b32_e64 v25, v216, v25, s[36:37]
	v_cndmask_b32_e64 v26, v216, v26, s[10:11]
	v_cndmask_b32_e64 v27, v216, v27, s[0:1]
	v_cndmask_b32_e64 v28, v216, v28, s[6:7]
	v_cndmask_b32_e64 v29, v216, v29, s[8:9]
	v_cndmask_b32_e64 v30, v216, v30, s[16:17]
	v_cndmask_b32_e64 v31, v216, v31, s[20:21]
	global_load_dwordx4 v[32:35], v[212:213], off offset:496
	global_load_dwordx4 v[36:39], v[212:213], off offset:512
	global_load_dwordx4 v[40:43], v[212:213], off offset:620
	global_load_dwordx4 v[44:47], v[212:213], off offset:636
	global_load_dwordx4 v[48:51], v[212:213], off offset:744
	global_load_dwordx4 v[52:55], v[212:213], off offset:760
	global_load_dwordx4 v[56:59], v[212:213], off offset:868
	global_load_dwordx4 v[60:63], v[212:213], off offset:884
	s_waitcnt vmcnt(0)
	v_mul_f32_e32 v32, 0x41000000, v32
	v_mul_f32_e32 v33, 0x41000000, v33
	v_mul_f32_e32 v34, 0x41000000, v34
	v_mul_f32_e32 v35, 0x41000000, v35
	v_mul_f32_e32 v36, 0x41000000, v36
	v_mul_f32_e32 v37, 0x41000000, v37
	v_mul_f32_e32 v38, 0x41000000, v38
	v_mul_f32_e32 v39, 0x41000000, v39
	v_cndmask_b32_e64 v32, v216, v32, s[26:27]
	v_cndmask_b32_e64 v33, v216, v33, s[36:37]
	v_cndmask_b32_e64 v34, v216, v34, s[10:11]
	v_cndmask_b32_e64 v35, v216, v35, s[0:1]
	v_cndmask_b32_e64 v36, v216, v36, s[6:7]
	v_cndmask_b32_e64 v37, v216, v37, s[8:9]
	v_cndmask_b32_e64 v38, v216, v38, s[16:17]
	v_cndmask_b32_e64 v39, v216, v39, s[20:21]
	v_mul_f32_e32 v40, 0x41000000, v40
	v_mul_f32_e32 v41, 0x41000000, v41
	v_mul_f32_e32 v42, 0x41000000, v42
	v_mul_f32_e32 v43, 0x41000000, v43
	v_mul_f32_e32 v44, 0x41000000, v44
	v_mul_f32_e32 v45, 0x41000000, v45
	v_mul_f32_e32 v46, 0x41000000, v46
	v_mul_f32_e32 v47, 0x41000000, v47
	v_cndmask_b32_e64 v40, v216, v40, s[26:27]
	v_cndmask_b32_e64 v41, v216, v41, s[36:37]
	v_cndmask_b32_e64 v42, v216, v42, s[10:11]
	v_cndmask_b32_e64 v43, v216, v43, s[0:1]
	v_cndmask_b32_e64 v44, v216, v44, s[6:7]
	v_cndmask_b32_e64 v45, v216, v45, s[8:9]
	v_cndmask_b32_e64 v46, v216, v46, s[16:17]
	v_cndmask_b32_e64 v47, v216, v47, s[20:21]
	v_mul_f32_e32 v48, 0x41000000, v48
	v_mul_f32_e32 v49, 0x41000000, v49
	v_mul_f32_e32 v50, 0x41000000, v50
	v_mul_f32_e32 v51, 0x41000000, v51
	v_mul_f32_e32 v52, 0x41000000, v52
	v_mul_f32_e32 v53, 0x41000000, v53
	v_mul_f32_e32 v54, 0x41000000, v54
	v_mul_f32_e32 v55, 0x41000000, v55
	v_cndmask_b32_e64 v48, v216, v48, s[26:27]
	v_cndmask_b32_e64 v49, v216, v49, s[36:37]
	v_cndmask_b32_e64 v50, v216, v50, s[10:11]
	v_cndmask_b32_e64 v51, v216, v51, s[0:1]
	v_cndmask_b32_e64 v52, v216, v52, s[6:7]
	v_cndmask_b32_e64 v53, v216, v53, s[8:9]
	v_cndmask_b32_e64 v54, v216, v54, s[16:17]
	v_cndmask_b32_e64 v55, v216, v55, s[20:21]
	v_mul_f32_e32 v56, 0x41000000, v56
	v_mul_f32_e32 v57, 0x41000000, v57
	v_mul_f32_e32 v58, 0x41000000, v58
	v_mul_f32_e32 v59, 0x41000000, v59
	v_mul_f32_e32 v60, 0x41000000, v60
	v_mul_f32_e32 v61, 0x41000000, v61
	v_mul_f32_e32 v62, 0x41000000, v62
	v_mul_f32_e32 v63, 0x41000000, v63
	v_cndmask_b32_e64 v56, v216, v56, s[26:27]
	v_cndmask_b32_e64 v57, v216, v57, s[36:37]
	v_cndmask_b32_e64 v58, v216, v58, s[10:11]
	v_cndmask_b32_e64 v59, v216, v59, s[0:1]
	v_cndmask_b32_e64 v60, v216, v60, s[6:7]
	v_cndmask_b32_e64 v61, v216, v61, s[8:9]
	v_cndmask_b32_e64 v62, v216, v62, s[16:17]
	v_cndmask_b32_e64 v63, v216, v63, s[20:21]
	v_readlane_b32 s0, v136, 0
	v_readlane_b32 s1, v136, 1
	v_readlane_b32 s6, v136, 2
	v_readlane_b32 s7, v136, 3
	v_readlane_b32 s8, v136, 4
	v_readlane_b32 s9, v136, 5
	v_mfma_f32_16x16x32_bf16 v[0:3], v[138:141], v[128:131], v[0:3]
	v_mfma_f32_16x16x32_bf16 v[0:3], v[142:145], v[132:135], v[0:3]
	global_load_dwordx4 v[138:141], v209, s[22:23] offset:2048
	global_load_dwordx4 v[142:145], v209, s[22:23] offset:2112
	s_add_u32 s22, s22, 0x3800
	s_addc_u32 s23, s23, 0
	v_mfma_f32_16x16x32_bf16 v[4:7], v[146:149], v[128:131], v[4:7]
	v_mfma_f32_16x16x32_bf16 v[4:7], v[150:153], v[132:135], v[4:7]
	global_load_dwordx4 v[146:149], v209, s[22:23] offset:2048
	global_load_dwordx4 v[150:153], v209, s[22:23] offset:2112
	s_add_u32 s22, s22, 0x34800
	s_addc_u32 s23, s23, 0
	v_mfma_f32_16x16x32_bf16 v[8:11], v[154:157], v[128:131], v[8:11]
	v_mfma_f32_16x16x32_bf16 v[8:11], v[158:161], v[132:135], v[8:11]
	global_load_dwordx4 v[154:157], v209, s[22:23] offset:2048
	global_load_dwordx4 v[158:161], v209, s[22:23] offset:2112
	s_add_u32 s22, s22, 0x3800
	s_addc_u32 s23, s23, 0
	v_mfma_f32_16x16x32_bf16 v[12:15], v[162:165], v[128:131], v[12:15]
	v_mfma_f32_16x16x32_bf16 v[12:15], v[166:169], v[132:135], v[12:15]
	global_load_dwordx4 v[162:165], v209, s[22:23] offset:2048
	global_load_dwordx4 v[166:169], v209, s[22:23] offset:2112
	s_add_u32 s22, s22, 0x34800
	s_addc_u32 s23, s23, 0
	v_mfma_f32_16x16x32_bf16 v[16:19], v[170:173], v[128:131], v[16:19]
	v_mfma_f32_16x16x32_bf16 v[16:19], v[174:177], v[132:135], v[16:19]
	global_load_dwordx4 v[170:173], v209, s[22:23] offset:2048
	global_load_dwordx4 v[174:177], v209, s[22:23] offset:2112
	s_add_u32 s22, s22, 0x3800
	s_addc_u32 s23, s23, 0
	v_mfma_f32_16x16x32_bf16 v[20:23], v[178:181], v[128:131], v[20:23]
	v_mfma_f32_16x16x32_bf16 v[20:23], v[182:185], v[132:135], v[20:23]
	global_load_dwordx4 v[178:181], v209, s[22:23] offset:2048
	global_load_dwordx4 v[182:185], v209, s[22:23] offset:2112
	s_add_u32 s22, s22, 0x34800
	s_addc_u32 s23, s23, 0
	s_waitcnt vmcnt(11)
	v_mfma_f32_16x16x32_bf16 v[24:27], v[138:141], v[128:131], v[24:27]
	s_waitcnt vmcnt(10)
	v_mfma_f32_16x16x32_bf16 v[24:27], v[142:145], v[132:135], v[24:27]
	global_load_dwordx4 v[138:141], v209, s[22:23] offset:2048
	global_load_dwordx4 v[142:145], v209, s[22:23] offset:2112
	s_add_u32 s22, s22, 0x3800
	s_addc_u32 s23, s23, 0
	s_waitcnt vmcnt(11)
	v_mfma_f32_16x16x32_bf16 v[28:31], v[146:149], v[128:131], v[28:31]
	s_waitcnt vmcnt(10)
	v_mfma_f32_16x16x32_bf16 v[28:31], v[150:153], v[132:135], v[28:31]
	global_load_dwordx4 v[146:149], v209, s[22:23] offset:2048
	global_load_dwordx4 v[150:153], v209, s[22:23] offset:2112
	s_add_u32 s22, s22, 0x34800
	s_addc_u32 s23, s23, 0
	s_waitcnt vmcnt(11)
	v_mfma_f32_16x16x32_bf16 v[32:35], v[154:157], v[128:131], v[32:35]
	s_waitcnt vmcnt(10)
	v_mfma_f32_16x16x32_bf16 v[32:35], v[158:161], v[132:135], v[32:35]
	global_load_dwordx4 v[154:157], v209, s[22:23] offset:2048
	global_load_dwordx4 v[158:161], v209, s[22:23] offset:2112
	s_add_u32 s22, s22, 0x3800
	s_addc_u32 s23, s23, 0
	s_waitcnt vmcnt(11)
	v_mfma_f32_16x16x32_bf16 v[36:39], v[162:165], v[128:131], v[36:39]
	s_waitcnt vmcnt(10)
	v_mfma_f32_16x16x32_bf16 v[36:39], v[166:169], v[132:135], v[36:39]
	global_load_dwordx4 v[162:165], v209, s[22:23] offset:2048
	global_load_dwordx4 v[166:169], v209, s[22:23] offset:2112
	s_waitcnt vmcnt(11)
	v_mfma_f32_16x16x32_bf16 v[40:43], v[170:173], v[128:131], v[40:43]
	s_waitcnt vmcnt(10)
	v_mfma_f32_16x16x32_bf16 v[40:43], v[174:177], v[132:135], v[40:43]
	s_barrier
	ds_read_b128 v[170:173], v211 offset:0
	ds_read_b128 v[174:177], v211 offset:1024
	s_waitcnt vmcnt(9)
	v_mfma_f32_16x16x32_bf16 v[44:47], v[178:181], v[128:131], v[44:47]
	s_waitcnt vmcnt(8)
	v_mfma_f32_16x16x32_bf16 v[44:47], v[182:185], v[132:135], v[44:47]
	ds_read_b128 v[178:181], v211 offset:2048
	ds_read_b128 v[182:185], v211 offset:3072
	s_waitcnt vmcnt(7)
	v_mfma_f32_16x16x32_bf16 v[48:51], v[138:141], v[128:131], v[48:51]
	s_waitcnt vmcnt(6)
	v_mfma_f32_16x16x32_bf16 v[48:51], v[142:145], v[132:135], v[48:51]
	ds_read_b128 v[138:141], v211 offset:4096
	ds_read_b128 v[142:145], v211 offset:5120
	s_waitcnt vmcnt(5)
	v_mfma_f32_16x16x32_bf16 v[52:55], v[146:149], v[128:131], v[52:55]
	s_waitcnt vmcnt(4)
	v_mfma_f32_16x16x32_bf16 v[52:55], v[150:153], v[132:135], v[52:55]
	ds_read_b128 v[146:149], v211 offset:6144
	ds_read_b128 v[150:153], v211 offset:7168
	s_waitcnt vmcnt(3)
	v_mfma_f32_16x16x32_bf16 v[56:59], v[154:157], v[128:131], v[56:59]
	s_waitcnt vmcnt(2)
	v_mfma_f32_16x16x32_bf16 v[56:59], v[158:161], v[132:135], v[56:59]
	ds_read_b128 v[154:157], v211 offset:8192
	ds_read_b128 v[158:161], v211 offset:9216
	s_waitcnt vmcnt(1)
	v_mfma_f32_16x16x32_bf16 v[60:63], v[162:165], v[128:131], v[60:63]
	s_waitcnt vmcnt(0)
	v_mfma_f32_16x16x32_bf16 v[60:63], v[166:169], v[132:135], v[60:63]
	ds_read_b128 v[162:165], v211 offset:10240
	ds_read_b128 v[166:169], v211 offset:11264
	s_waitcnt lgkmcnt(11)
	v_mfma_f32_16x16x32_bf16 v[64:67], v[170:173], v[128:131], 0
	s_waitcnt lgkmcnt(10)
	v_mfma_f32_16x16x32_bf16 v[64:67], v[174:177], v[132:135], v[64:67]
	ds_read_b128 v[170:173], v211 offset:12288
	ds_read_b128 v[174:177], v211 offset:13312
	s_waitcnt lgkmcnt(11)
	v_mfma_f32_16x16x32_bf16 v[68:71], v[178:181], v[128:131], 0
	s_waitcnt lgkmcnt(10)
	v_mfma_f32_16x16x32_bf16 v[68:71], v[182:185], v[132:135], v[68:71]
	ds_read_b128 v[178:181], v211 offset:14336
	ds_read_b128 v[182:185], v211 offset:15360
	s_waitcnt lgkmcnt(11)
	v_mfma_f32_16x16x32_bf16 v[72:75], v[138:141], v[128:131], 0
	s_waitcnt lgkmcnt(10)
	v_mfma_f32_16x16x32_bf16 v[72:75], v[142:145], v[132:135], v[72:75]
	ds_read_b128 v[138:141], v211 offset:16384
	ds_read_b128 v[142:145], v211 offset:17408
	s_waitcnt lgkmcnt(11)
	v_mfma_f32_16x16x32_bf16 v[76:79], v[146:149], v[128:131], 0
	s_waitcnt lgkmcnt(10)
	v_mfma_f32_16x16x32_bf16 v[76:79], v[150:153], v[132:135], v[76:79]
	ds_read_b128 v[146:149], v211 offset:18432
	ds_read_b128 v[150:153], v211 offset:19456
	s_waitcnt lgkmcnt(11)
	v_mfma_f32_16x16x32_bf16 v[80:83], v[154:157], v[128:131], 0
	s_waitcnt lgkmcnt(10)
	v_mfma_f32_16x16x32_bf16 v[80:83], v[158:161], v[132:135], v[80:83]
	ds_read_b128 v[154:157], v211 offset:20480
	ds_read_b128 v[158:161], v211 offset:21504
	s_waitcnt lgkmcnt(11)
	v_mfma_f32_16x16x32_bf16 v[84:87], v[162:165], v[128:131], 0
	s_waitcnt lgkmcnt(10)
	v_mfma_f32_16x16x32_bf16 v[84:87], v[166:169], v[132:135], v[84:87]
	ds_read_b128 v[162:165], v211 offset:22528
	ds_read_b128 v[166:169], v211 offset:23552
	s_waitcnt lgkmcnt(11)
	v_mfma_f32_16x16x32_bf16 v[88:91], v[170:173], v[128:131], 0
	s_waitcnt lgkmcnt(10)
	v_mfma_f32_16x16x32_bf16 v[88:91], v[174:177], v[132:135], v[88:91]
	ds_read_b128 v[170:173], v211 offset:24576
	ds_read_b128 v[174:177], v211 offset:25600
	s_waitcnt lgkmcnt(11)
	v_mfma_f32_16x16x32_bf16 v[92:95], v[178:181], v[128:131], 0
	s_waitcnt lgkmcnt(10)
	v_mfma_f32_16x16x32_bf16 v[92:95], v[182:185], v[132:135], v[92:95]
	ds_read_b128 v[178:181], v211 offset:26624
	ds_read_b128 v[182:185], v211 offset:27648
	s_waitcnt lgkmcnt(11)
	v_mfma_f32_16x16x32_bf16 v[96:99], v[138:141], v[128:131], 0
	s_waitcnt lgkmcnt(10)
	v_mfma_f32_16x16x32_bf16 v[96:99], v[142:145], v[132:135], v[96:99]
	ds_read_b128 v[138:141], v211 offset:28672
	ds_read_b128 v[142:145], v211 offset:29696
	s_waitcnt lgkmcnt(11)
	v_mfma_f32_16x16x32_bf16 v[100:103], v[146:149], v[128:131], 0
	s_waitcnt lgkmcnt(10)
	v_mfma_f32_16x16x32_bf16 v[100:103], v[150:153], v[132:135], v[100:103]
	ds_read_b128 v[146:149], v211 offset:30720
	ds_read_b128 v[150:153], v211 offset:31744
	s_waitcnt lgkmcnt(11)
	v_mfma_f32_16x16x32_bf16 v[104:107], v[154:157], v[128:131], 0
	s_waitcnt lgkmcnt(10)
	v_mfma_f32_16x16x32_bf16 v[104:107], v[158:161], v[132:135], v[104:107]
	s_waitcnt lgkmcnt(9)
	v_mfma_f32_16x16x32_bf16 v[108:111], v[162:165], v[128:131], 0
	s_waitcnt lgkmcnt(8)
	v_mfma_f32_16x16x32_bf16 v[108:111], v[166:169], v[132:135], v[108:111]
	s_waitcnt lgkmcnt(7)
	v_mfma_f32_16x16x32_bf16 v[112:115], v[170:173], v[128:131], 0
	s_waitcnt lgkmcnt(6)
	v_mfma_f32_16x16x32_bf16 v[112:115], v[174:177], v[132:135], v[112:115]
	s_waitcnt lgkmcnt(5)
	v_mfma_f32_16x16x32_bf16 v[116:119], v[178:181], v[128:131], 0
	s_waitcnt lgkmcnt(4)
	v_mfma_f32_16x16x32_bf16 v[116:119], v[182:185], v[132:135], v[116:119]
	s_waitcnt lgkmcnt(3)
	v_mfma_f32_16x16x32_bf16 v[120:123], v[138:141], v[128:131], 0
	s_waitcnt lgkmcnt(2)
	v_mfma_f32_16x16x32_bf16 v[120:123], v[142:145], v[132:135], v[120:123]
	s_waitcnt lgkmcnt(1)
	v_mfma_f32_16x16x32_bf16 v[124:127], v[146:149], v[128:131], 0
	s_waitcnt lgkmcnt(0)
	v_mfma_f32_16x16x32_bf16 v[124:127], v[150:153], v[132:135], v[124:127]
	s_bfe_u32 s10, s86, 0x50005
	s_lshl_b32 s10, s10, 1
	s_sub_i32 s10, s10, 4
	s_max_i32 s10, s10, 0
	s_min_i32 s10, s10, 56
	s_sub_i32 s10, s7, s10
	s_lshl_b32 s10, s10, 13
	s_add_i32 s10, s10, 0x10000
	s_lshr_b32 s11, s9, 3
	v_add_u32_e32 v210, s11, v207
	v_lshrrev_b32_e32 v209, 1, v206
	v_xor_b32_e32 v210, v210, v209
	v_lshlrev_b32_e32 v210, 4, v210
	v_lshl_add_u32 v210, v206, 7, v210
	v_add_u32_e32 v210, s10, v210
	s_lshl_b32 s10, s8, 8
	s_lshl_b32 s11, s6, 6
	s_add_i32 s10, s10, s11
	s_lshl_b32 s11, s10, 13
	s_lshl_b32 s38, s7, 7
	s_add_i32 s11, s11, s38
	s_lshl_b32 s38, s9, 1
	s_add_i32 s11, s11, s38
	s_add_u32 s11, s11, 0x9a00000
	s_add_u32 s16, s4, s11
	s_addc_u32 s17, s5, 0
	s_add_u32 s18, s16, 0x20000
	s_addc_u32 s19, s17, 0
	s_add_u32 s20, s18, 0x20000
	s_addc_u32 s21, s19, 0
	s_add_u32 s22, s20, 0x20000
	s_addc_u32 s23, s21, 0
	s_lshl_b32 s11, s10, 9
	s_add_u32 s11, s11, 0xa200000
	s_add_u32 s24, s4, s11
	s_addc_u32 s25, s5, 0
	s_add_u32 s26, s24, 0x2000
	s_addc_u32 s27, s25, 0
	s_add_u32 s36, s26, 0x2000
	s_addc_u32 s37, s27, 0
	s_lshl_b32 s10, s8, 12
	s_lshl_b32 s11, s1, 6
	s_add_i32 s10, s10, s11
	s_lshl_b32 s11, s0, 4
	s_add_i32 s10, s10, s11
	s_addk_i32 s10, 0x400
	s_mul_i32 s10, s10, 0x600
	s_lshl_b32 s11, s6, 7
	s_add_i32 s10, s10, s11
	s_add_u32 s38, s10, 0xdf00400
	s_add_u32 s0, s36, 0x2000
	s_addc_u32 s1, s37, 0
	s_nop 7
	v_max3_f32 v214, v0, v1, v2
	v_max3_f32 v214, v214, v3, v4
	v_max3_f32 v214, v214, v5, v6
	v_max3_f32 v214, v214, v7, v8
	v_max3_f32 v214, v214, v9, v10
	v_max3_f32 v214, v214, v11, v12
	v_max3_f32 v214, v214, v13, v14
	v_max3_f32 v214, v214, v15, v16
	v_max3_f32 v214, v214, v17, v18
	v_max3_f32 v214, v214, v19, v20
	v_max3_f32 v214, v214, v21, v22
	v_max3_f32 v214, v214, v23, v24
	v_max3_f32 v214, v214, v25, v26
	v_max3_f32 v214, v214, v27, v28
	v_max3_f32 v214, v214, v29, v30
	v_max3_f32 v214, v214, v31, v32
	v_max3_f32 v214, v214, v33, v34
	v_max3_f32 v214, v214, v35, v36
	v_max3_f32 v214, v214, v37, v38
	v_max3_f32 v214, v214, v39, v40
	v_max3_f32 v214, v214, v41, v42
	v_max3_f32 v214, v214, v43, v44
	v_max3_f32 v214, v214, v45, v46
	v_max3_f32 v214, v214, v47, v48
	v_max3_f32 v214, v214, v49, v50
	v_max3_f32 v214, v214, v51, v52
	v_max3_f32 v214, v214, v53, v54
	v_max3_f32 v214, v214, v55, v56
	v_max3_f32 v214, v214, v57, v58
	v_max3_f32 v214, v214, v59, v60
	v_max3_f32 v214, v214, v61, v62
	v_max3_f32 v214, v214, v63, v64
	v_max3_f32 v214, v214, v65, v66
	v_max3_f32 v214, v214, v67, v68
	v_max3_f32 v214, v214, v69, v70
	v_max3_f32 v214, v214, v71, v72
	v_max3_f32 v214, v214, v73, v74
	v_max3_f32 v214, v214, v75, v76
	v_max3_f32 v214, v214, v77, v78
	v_max3_f32 v214, v214, v79, v80
	v_max3_f32 v214, v214, v81, v82
	v_max3_f32 v214, v214, v83, v84
	v_max3_f32 v214, v214, v85, v86
	v_max3_f32 v214, v214, v87, v88
	v_max3_f32 v214, v214, v89, v90
	v_max3_f32 v214, v214, v91, v92
	v_max3_f32 v214, v214, v93, v94
	v_max3_f32 v214, v214, v95, v96
	v_max3_f32 v214, v214, v97, v98
	v_max3_f32 v214, v214, v99, v100
	v_max3_f32 v214, v214, v101, v102
	v_max3_f32 v214, v214, v103, v104
	v_max3_f32 v214, v214, v105, v106
	v_max3_f32 v214, v214, v107, v108
	v_max3_f32 v214, v214, v109, v110
	v_max3_f32 v214, v214, v111, v112
	v_max3_f32 v214, v214, v113, v114
	v_max3_f32 v214, v214, v115, v116
	v_max3_f32 v214, v214, v117, v118
	v_max3_f32 v214, v214, v119, v120
	v_max3_f32 v214, v214, v121, v122
	v_max3_f32 v214, v214, v123, v124
	v_max3_f32 v214, v214, v125, v126
	v_max_f32_e32 v214, v214, v127
	v_xor_b32_e32 v215, 16, v205
	v_lshlrev_b32_e32 v215, 2, v215
	v_xor_b32_e32 v216, 32, v205
	v_lshlrev_b32_e32 v216, 2, v216
	ds_bpermute_b32 v136, v215, v214
	s_waitcnt lgkmcnt(0)
	v_max_f32_e32 v214, v214, v136
	ds_bpermute_b32 v136, v216, v214
	s_waitcnt lgkmcnt(0)
	v_max_f32_e32 v214, v214, v136
	v_mul_f32_e32 v214, 0xbe38aa3b, v214
	s_mov_b32 s10, 0x3e38aa3b
	v_mov_b32_e32 v212, 0
	v_mov_b32_e32 v213, 0
	v_fma_f32 v0, v0, s10, v214
	v_fma_f32 v1, v1, s10, v214
	v_fma_f32 v2, v2, s10, v214
	v_fma_f32 v3, v3, s10, v214
	v_fma_f32 v4, v4, s10, v214
	v_fma_f32 v5, v5, s10, v214
	v_fma_f32 v6, v6, s10, v214
	v_fma_f32 v7, v7, s10, v214
	v_exp_f32_e32 v0, v0
	v_exp_f32_e32 v1, v1
	v_exp_f32_e32 v2, v2
	v_exp_f32_e32 v3, v3
	v_exp_f32_e32 v4, v4
	v_exp_f32_e32 v5, v5
	v_exp_f32_e32 v6, v6
	v_exp_f32_e32 v7, v7
	s_nop 0
	v_add_f32_e32 v212, v212, v0
	v_add_f32_e32 v213, v213, v1
	v_add_f32_e32 v212, v212, v2
	v_add_f32_e32 v213, v213, v3
	v_add_f32_e32 v212, v212, v4
	v_add_f32_e32 v213, v213, v5
	v_add_f32_e32 v212, v212, v6
	v_add_f32_e32 v213, v213, v7
	v_cvt_pk_bf16_f32 v0, v0, v1
	v_cvt_pk_bf16_f32 v1, v2, v3
	v_cvt_pk_bf16_f32 v2, v4, v5
	v_cvt_pk_bf16_f32 v3, v6, v7
	v_fma_f32 v8, v8, s10, v214
	v_fma_f32 v9, v9, s10, v214
	v_fma_f32 v10, v10, s10, v214
	v_fma_f32 v11, v11, s10, v214
	v_fma_f32 v12, v12, s10, v214
	v_fma_f32 v13, v13, s10, v214
	v_fma_f32 v14, v14, s10, v214
	v_fma_f32 v15, v15, s10, v214
	v_exp_f32_e32 v8, v8
	v_exp_f32_e32 v9, v9
	v_exp_f32_e32 v10, v10
	v_exp_f32_e32 v11, v11
	v_exp_f32_e32 v12, v12
	v_exp_f32_e32 v13, v13
	v_exp_f32_e32 v14, v14
	v_exp_f32_e32 v15, v15
	s_nop 0
	v_add_f32_e32 v212, v212, v8
	v_add_f32_e32 v213, v213, v9
	v_add_f32_e32 v212, v212, v10
	v_add_f32_e32 v213, v213, v11
	v_add_f32_e32 v212, v212, v12
	v_add_f32_e32 v213, v213, v13
	v_add_f32_e32 v212, v212, v14
	v_add_f32_e32 v213, v213, v15
	v_cvt_pk_bf16_f32 v8, v8, v9
	v_cvt_pk_bf16_f32 v9, v10, v11
	v_cvt_pk_bf16_f32 v10, v12, v13
	v_cvt_pk_bf16_f32 v11, v14, v15
	v_fma_f32 v16, v16, s10, v214
	v_fma_f32 v17, v17, s10, v214
	v_fma_f32 v18, v18, s10, v214
	v_fma_f32 v19, v19, s10, v214
	v_fma_f32 v20, v20, s10, v214
	v_fma_f32 v21, v21, s10, v214
	v_fma_f32 v22, v22, s10, v214
	v_fma_f32 v23, v23, s10, v214
	v_exp_f32_e32 v16, v16
	v_exp_f32_e32 v17, v17
	v_exp_f32_e32 v18, v18
	v_exp_f32_e32 v19, v19
	v_exp_f32_e32 v20, v20
	v_exp_f32_e32 v21, v21
	v_exp_f32_e32 v22, v22
	v_exp_f32_e32 v23, v23
	s_nop 0
	v_add_f32_e32 v212, v212, v16
	v_add_f32_e32 v213, v213, v17
	v_add_f32_e32 v212, v212, v18
	v_add_f32_e32 v213, v213, v19
	v_add_f32_e32 v212, v212, v20
	v_add_f32_e32 v213, v213, v21
	v_add_f32_e32 v212, v212, v22
	v_add_f32_e32 v213, v213, v23
	v_cvt_pk_bf16_f32 v16, v16, v17
	v_cvt_pk_bf16_f32 v17, v18, v19
	v_cvt_pk_bf16_f32 v18, v20, v21
	v_cvt_pk_bf16_f32 v19, v22, v23
	v_fma_f32 v24, v24, s10, v214
	v_fma_f32 v25, v25, s10, v214
	v_fma_f32 v26, v26, s10, v214
	v_fma_f32 v27, v27, s10, v214
	v_fma_f32 v28, v28, s10, v214
	v_fma_f32 v29, v29, s10, v214
	v_fma_f32 v30, v30, s10, v214
	v_fma_f32 v31, v31, s10, v214
	v_exp_f32_e32 v24, v24
	v_exp_f32_e32 v25, v25
	v_exp_f32_e32 v26, v26
	v_exp_f32_e32 v27, v27
	v_exp_f32_e32 v28, v28
	v_exp_f32_e32 v29, v29
	v_exp_f32_e32 v30, v30
	v_exp_f32_e32 v31, v31
	s_nop 0
	v_add_f32_e32 v212, v212, v24
	v_add_f32_e32 v213, v213, v25
	v_add_f32_e32 v212, v212, v26
	v_add_f32_e32 v213, v213, v27
	v_add_f32_e32 v212, v212, v28
	v_add_f32_e32 v213, v213, v29
	v_add_f32_e32 v212, v212, v30
	v_add_f32_e32 v213, v213, v31
	v_cvt_pk_bf16_f32 v24, v24, v25
	v_cvt_pk_bf16_f32 v25, v26, v27
	v_cvt_pk_bf16_f32 v26, v28, v29
	v_cvt_pk_bf16_f32 v27, v30, v31
	v_fma_f32 v32, v32, s10, v214
	v_fma_f32 v33, v33, s10, v214
	v_fma_f32 v34, v34, s10, v214
	v_fma_f32 v35, v35, s10, v214
	v_fma_f32 v36, v36, s10, v214
	v_fma_f32 v37, v37, s10, v214
	v_fma_f32 v38, v38, s10, v214
	v_fma_f32 v39, v39, s10, v214
	v_exp_f32_e32 v32, v32
	v_exp_f32_e32 v33, v33
	v_exp_f32_e32 v34, v34
	v_exp_f32_e32 v35, v35
	v_exp_f32_e32 v36, v36
	v_exp_f32_e32 v37, v37
	v_exp_f32_e32 v38, v38
	v_exp_f32_e32 v39, v39
	s_nop 0
	v_add_f32_e32 v212, v212, v32
	v_add_f32_e32 v213, v213, v33
	v_add_f32_e32 v212, v212, v34
	v_add_f32_e32 v213, v213, v35
	v_add_f32_e32 v212, v212, v36
	v_add_f32_e32 v213, v213, v37
	v_add_f32_e32 v212, v212, v38
	v_add_f32_e32 v213, v213, v39
	v_cvt_pk_bf16_f32 v32, v32, v33
	v_cvt_pk_bf16_f32 v33, v34, v35
	v_cvt_pk_bf16_f32 v34, v36, v37
	v_cvt_pk_bf16_f32 v35, v38, v39
	v_fma_f32 v40, v40, s10, v214
	v_fma_f32 v41, v41, s10, v214
	v_fma_f32 v42, v42, s10, v214
	v_fma_f32 v43, v43, s10, v214
	v_fma_f32 v44, v44, s10, v214
	v_fma_f32 v45, v45, s10, v214
	v_fma_f32 v46, v46, s10, v214
	v_fma_f32 v47, v47, s10, v214
	v_exp_f32_e32 v40, v40
	v_exp_f32_e32 v41, v41
	v_exp_f32_e32 v42, v42
	v_exp_f32_e32 v43, v43
	v_exp_f32_e32 v44, v44
	v_exp_f32_e32 v45, v45
	v_exp_f32_e32 v46, v46
	v_exp_f32_e32 v47, v47
	s_nop 0
	v_add_f32_e32 v212, v212, v40
	v_add_f32_e32 v213, v213, v41
	v_add_f32_e32 v212, v212, v42
	v_add_f32_e32 v213, v213, v43
	v_add_f32_e32 v212, v212, v44
	v_add_f32_e32 v213, v213, v45
	v_add_f32_e32 v212, v212, v46
	v_add_f32_e32 v213, v213, v47
	v_cvt_pk_bf16_f32 v40, v40, v41
	v_cvt_pk_bf16_f32 v41, v42, v43
	v_cvt_pk_bf16_f32 v42, v44, v45
	v_cvt_pk_bf16_f32 v43, v46, v47
	v_fma_f32 v48, v48, s10, v214
	v_fma_f32 v49, v49, s10, v214
	v_fma_f32 v50, v50, s10, v214
	v_fma_f32 v51, v51, s10, v214
	v_fma_f32 v52, v52, s10, v214
	v_fma_f32 v53, v53, s10, v214
	v_fma_f32 v54, v54, s10, v214
	v_fma_f32 v55, v55, s10, v214
	v_exp_f32_e32 v48, v48
	v_exp_f32_e32 v49, v49
	v_exp_f32_e32 v50, v50
	v_exp_f32_e32 v51, v51
	v_exp_f32_e32 v52, v52
	v_exp_f32_e32 v53, v53
	v_exp_f32_e32 v54, v54
	v_exp_f32_e32 v55, v55
	s_nop 0
	v_add_f32_e32 v212, v212, v48
	v_add_f32_e32 v213, v213, v49
	v_add_f32_e32 v212, v212, v50
	v_add_f32_e32 v213, v213, v51
	v_add_f32_e32 v212, v212, v52
	v_add_f32_e32 v213, v213, v53
	v_add_f32_e32 v212, v212, v54
	v_add_f32_e32 v213, v213, v55
	v_cvt_pk_bf16_f32 v48, v48, v49
	v_cvt_pk_bf16_f32 v49, v50, v51
	v_cvt_pk_bf16_f32 v50, v52, v53
	v_cvt_pk_bf16_f32 v51, v54, v55
	v_fma_f32 v56, v56, s10, v214
	v_fma_f32 v57, v57, s10, v214
	v_fma_f32 v58, v58, s10, v214
	v_fma_f32 v59, v59, s10, v214
	v_fma_f32 v60, v60, s10, v214
	v_fma_f32 v61, v61, s10, v214
	v_fma_f32 v62, v62, s10, v214
	v_fma_f32 v63, v63, s10, v214
	v_exp_f32_e32 v56, v56
	v_exp_f32_e32 v57, v57
	v_exp_f32_e32 v58, v58
	v_exp_f32_e32 v59, v59
	v_exp_f32_e32 v60, v60
	v_exp_f32_e32 v61, v61
	v_exp_f32_e32 v62, v62
	v_exp_f32_e32 v63, v63
	s_nop 0
	v_add_f32_e32 v212, v212, v56
	v_add_f32_e32 v213, v213, v57
	v_add_f32_e32 v212, v212, v58
	v_add_f32_e32 v213, v213, v59
	v_add_f32_e32 v212, v212, v60
	v_add_f32_e32 v213, v213, v61
	v_add_f32_e32 v212, v212, v62
	v_add_f32_e32 v213, v213, v63
	v_cvt_pk_bf16_f32 v56, v56, v57
	v_cvt_pk_bf16_f32 v57, v58, v59
	v_cvt_pk_bf16_f32 v58, v60, v61
	v_cvt_pk_bf16_f32 v59, v62, v63
	v_fma_f32 v64, v64, s10, v214
	v_fma_f32 v65, v65, s10, v214
	v_fma_f32 v66, v66, s10, v214
	v_fma_f32 v67, v67, s10, v214
	v_fma_f32 v68, v68, s10, v214
	v_fma_f32 v69, v69, s10, v214
	v_fma_f32 v70, v70, s10, v214
	v_fma_f32 v71, v71, s10, v214
	v_exp_f32_e32 v64, v64
	v_exp_f32_e32 v65, v65
	v_exp_f32_e32 v66, v66
	v_exp_f32_e32 v67, v67
	v_exp_f32_e32 v68, v68
	v_exp_f32_e32 v69, v69
	v_exp_f32_e32 v70, v70
	v_exp_f32_e32 v71, v71
	s_nop 0
	v_add_f32_e32 v212, v212, v64
	v_add_f32_e32 v213, v213, v65
	v_add_f32_e32 v212, v212, v66
	v_add_f32_e32 v213, v213, v67
	v_add_f32_e32 v212, v212, v68
	v_add_f32_e32 v213, v213, v69
	v_add_f32_e32 v212, v212, v70
	v_add_f32_e32 v213, v213, v71
	v_cvt_pk_bf16_f32 v64, v64, v65
	v_cvt_pk_bf16_f32 v65, v66, v67
	v_cvt_pk_bf16_f32 v66, v68, v69
	v_cvt_pk_bf16_f32 v67, v70, v71
	v_fma_f32 v72, v72, s10, v214
	v_fma_f32 v73, v73, s10, v214
	v_fma_f32 v74, v74, s10, v214
	v_fma_f32 v75, v75, s10, v214
	v_fma_f32 v76, v76, s10, v214
	v_fma_f32 v77, v77, s10, v214
	v_fma_f32 v78, v78, s10, v214
	v_fma_f32 v79, v79, s10, v214
	v_exp_f32_e32 v72, v72
	v_exp_f32_e32 v73, v73
	v_exp_f32_e32 v74, v74
	v_exp_f32_e32 v75, v75
	v_exp_f32_e32 v76, v76
	v_exp_f32_e32 v77, v77
	v_exp_f32_e32 v78, v78
	v_exp_f32_e32 v79, v79
	s_nop 0
	v_add_f32_e32 v212, v212, v72
	v_add_f32_e32 v213, v213, v73
	v_add_f32_e32 v212, v212, v74
	v_add_f32_e32 v213, v213, v75
	v_add_f32_e32 v212, v212, v76
	v_add_f32_e32 v213, v213, v77
	v_add_f32_e32 v212, v212, v78
	v_add_f32_e32 v213, v213, v79
	v_cvt_pk_bf16_f32 v72, v72, v73
	v_cvt_pk_bf16_f32 v73, v74, v75
	v_cvt_pk_bf16_f32 v74, v76, v77
	v_cvt_pk_bf16_f32 v75, v78, v79
	v_fma_f32 v80, v80, s10, v214
	v_fma_f32 v81, v81, s10, v214
	v_fma_f32 v82, v82, s10, v214
	v_fma_f32 v83, v83, s10, v214
	v_fma_f32 v84, v84, s10, v214
	v_fma_f32 v85, v85, s10, v214
	v_fma_f32 v86, v86, s10, v214
	v_fma_f32 v87, v87, s10, v214
	v_exp_f32_e32 v80, v80
	v_exp_f32_e32 v81, v81
	v_exp_f32_e32 v82, v82
	v_exp_f32_e32 v83, v83
	v_exp_f32_e32 v84, v84
	v_exp_f32_e32 v85, v85
	v_exp_f32_e32 v86, v86
	v_exp_f32_e32 v87, v87
	s_nop 0
	v_add_f32_e32 v212, v212, v80
	v_add_f32_e32 v213, v213, v81
	v_add_f32_e32 v212, v212, v82
	v_add_f32_e32 v213, v213, v83
	v_add_f32_e32 v212, v212, v84
	v_add_f32_e32 v213, v213, v85
	v_add_f32_e32 v212, v212, v86
	v_add_f32_e32 v213, v213, v87
	v_cvt_pk_bf16_f32 v80, v80, v81
	v_cvt_pk_bf16_f32 v81, v82, v83
	v_cvt_pk_bf16_f32 v82, v84, v85
	v_cvt_pk_bf16_f32 v83, v86, v87
	v_fma_f32 v88, v88, s10, v214
	v_fma_f32 v89, v89, s10, v214
	v_fma_f32 v90, v90, s10, v214
	v_fma_f32 v91, v91, s10, v214
	v_fma_f32 v92, v92, s10, v214
	v_fma_f32 v93, v93, s10, v214
	v_fma_f32 v94, v94, s10, v214
	v_fma_f32 v95, v95, s10, v214
	v_exp_f32_e32 v88, v88
	v_exp_f32_e32 v89, v89
	v_exp_f32_e32 v90, v90
	v_exp_f32_e32 v91, v91
	v_exp_f32_e32 v92, v92
	v_exp_f32_e32 v93, v93
	v_exp_f32_e32 v94, v94
	v_exp_f32_e32 v95, v95
	s_nop 0
	v_add_f32_e32 v212, v212, v88
	v_add_f32_e32 v213, v213, v89
	v_add_f32_e32 v212, v212, v90
	v_add_f32_e32 v213, v213, v91
	v_add_f32_e32 v212, v212, v92
	v_add_f32_e32 v213, v213, v93
	v_add_f32_e32 v212, v212, v94
	v_add_f32_e32 v213, v213, v95
	v_cvt_pk_bf16_f32 v88, v88, v89
	v_cvt_pk_bf16_f32 v89, v90, v91
	v_cvt_pk_bf16_f32 v90, v92, v93
	v_cvt_pk_bf16_f32 v91, v94, v95
	v_fma_f32 v96, v96, s10, v214
	v_fma_f32 v97, v97, s10, v214
	v_fma_f32 v98, v98, s10, v214
	v_fma_f32 v99, v99, s10, v214
	v_fma_f32 v100, v100, s10, v214
	v_fma_f32 v101, v101, s10, v214
	v_fma_f32 v102, v102, s10, v214
	v_fma_f32 v103, v103, s10, v214
	v_exp_f32_e32 v96, v96
	v_exp_f32_e32 v97, v97
	v_exp_f32_e32 v98, v98
	v_exp_f32_e32 v99, v99
	v_exp_f32_e32 v100, v100
	v_exp_f32_e32 v101, v101
	v_exp_f32_e32 v102, v102
	v_exp_f32_e32 v103, v103
	s_nop 0
	v_add_f32_e32 v212, v212, v96
	v_add_f32_e32 v213, v213, v97
	v_add_f32_e32 v212, v212, v98
	v_add_f32_e32 v213, v213, v99
	v_add_f32_e32 v212, v212, v100
	v_add_f32_e32 v213, v213, v101
	v_add_f32_e32 v212, v212, v102
	v_add_f32_e32 v213, v213, v103
	v_cvt_pk_bf16_f32 v96, v96, v97
	v_cvt_pk_bf16_f32 v97, v98, v99
	v_cvt_pk_bf16_f32 v98, v100, v101
	v_cvt_pk_bf16_f32 v99, v102, v103
	v_fma_f32 v104, v104, s10, v214
	v_fma_f32 v105, v105, s10, v214
	v_fma_f32 v106, v106, s10, v214
	v_fma_f32 v107, v107, s10, v214
	v_fma_f32 v108, v108, s10, v214
	v_fma_f32 v109, v109, s10, v214
	v_fma_f32 v110, v110, s10, v214
	v_fma_f32 v111, v111, s10, v214
	v_exp_f32_e32 v104, v104
	v_exp_f32_e32 v105, v105
	v_exp_f32_e32 v106, v106
	v_exp_f32_e32 v107, v107
	v_exp_f32_e32 v108, v108
	v_exp_f32_e32 v109, v109
	v_exp_f32_e32 v110, v110
	v_exp_f32_e32 v111, v111
	s_nop 0
	v_add_f32_e32 v212, v212, v104
	v_add_f32_e32 v213, v213, v105
	v_add_f32_e32 v212, v212, v106
	v_add_f32_e32 v213, v213, v107
	v_add_f32_e32 v212, v212, v108
	v_add_f32_e32 v213, v213, v109
	v_add_f32_e32 v212, v212, v110
	v_add_f32_e32 v213, v213, v111
	v_cvt_pk_bf16_f32 v104, v104, v105
	v_cvt_pk_bf16_f32 v105, v106, v107
	v_cvt_pk_bf16_f32 v106, v108, v109
	v_cvt_pk_bf16_f32 v107, v110, v111
	v_fma_f32 v112, v112, s10, v214
	v_fma_f32 v113, v113, s10, v214
	v_fma_f32 v114, v114, s10, v214
	v_fma_f32 v115, v115, s10, v214
	v_fma_f32 v116, v116, s10, v214
	v_fma_f32 v117, v117, s10, v214
	v_fma_f32 v118, v118, s10, v214
	v_fma_f32 v119, v119, s10, v214
	v_exp_f32_e32 v112, v112
	v_exp_f32_e32 v113, v113
	v_exp_f32_e32 v114, v114
	v_exp_f32_e32 v115, v115
	v_exp_f32_e32 v116, v116
	v_exp_f32_e32 v117, v117
	v_exp_f32_e32 v118, v118
	v_exp_f32_e32 v119, v119
	s_nop 0
	v_add_f32_e32 v212, v212, v112
	v_add_f32_e32 v213, v213, v113
	v_add_f32_e32 v212, v212, v114
	v_add_f32_e32 v213, v213, v115
	v_add_f32_e32 v212, v212, v116
	v_add_f32_e32 v213, v213, v117
	v_add_f32_e32 v212, v212, v118
	v_add_f32_e32 v213, v213, v119
	v_cvt_pk_bf16_f32 v112, v112, v113
	v_cvt_pk_bf16_f32 v113, v114, v115
	v_cvt_pk_bf16_f32 v114, v116, v117
	v_cvt_pk_bf16_f32 v115, v118, v119
	v_fma_f32 v120, v120, s10, v214
	v_fma_f32 v121, v121, s10, v214
	v_fma_f32 v122, v122, s10, v214
	v_fma_f32 v123, v123, s10, v214
	v_fma_f32 v124, v124, s10, v214
	v_fma_f32 v125, v125, s10, v214
	v_fma_f32 v126, v126, s10, v214
	v_fma_f32 v127, v127, s10, v214
	v_exp_f32_e32 v120, v120
	v_exp_f32_e32 v121, v121
	v_exp_f32_e32 v122, v122
	v_exp_f32_e32 v123, v123
	v_exp_f32_e32 v124, v124
	v_exp_f32_e32 v125, v125
	v_exp_f32_e32 v126, v126
	v_exp_f32_e32 v127, v127
	s_nop 0
	v_add_f32_e32 v212, v212, v120
	v_add_f32_e32 v213, v213, v121
	v_add_f32_e32 v212, v212, v122
	v_add_f32_e32 v213, v213, v123
	v_add_f32_e32 v212, v212, v124
	v_add_f32_e32 v213, v213, v125
	v_add_f32_e32 v212, v212, v126
	v_add_f32_e32 v213, v213, v127
	v_cvt_pk_bf16_f32 v120, v120, v121
	v_cvt_pk_bf16_f32 v121, v122, v123
	v_cvt_pk_bf16_f32 v122, v124, v125
	v_cvt_pk_bf16_f32 v123, v126, v127
	v_add_f32_e32 v212, v212, v213
	ds_read_b128 v[138:141], v210 offset:0
	ds_read_b128 v[142:145], v210 offset:2048
	ds_read_b128 v[146:149], v210 offset:4096
	ds_read_b128 v[150:153], v210 offset:6144
	ds_read_b128 v[154:157], v210 offset:8192
	ds_read_b128 v[158:161], v210 offset:10240
	ds_read_b128 v[162:165], v210 offset:12288
	ds_read_b128 v[166:169], v210 offset:14336
	s_waitcnt lgkmcnt(7)
	v_mfma_f32_16x16x32_bf16 v[128:131], v[138:141], v[0:3], 0
	ds_read_b128 v[170:173], v210 offset:16384
	s_waitcnt lgkmcnt(7)
	v_mfma_f32_16x16x32_bf16 v[132:135], v[142:145], v[0:3], 0
	ds_read_b128 v[174:177], v210 offset:18432
	s_waitcnt lgkmcnt(7)
	v_mfma_f32_16x16x32_bf16 v[178:181], v[146:149], v[0:3], 0
	ds_read_b128 v[4:7], v210 offset:20480
	s_waitcnt lgkmcnt(7)
	v_mfma_f32_16x16x32_bf16 v[182:185], v[150:153], v[0:3], 0
	ds_read_b128 v[12:15], v210 offset:22528
	s_waitcnt lgkmcnt(7)
	v_mfma_f32_16x16x32_bf16 v[128:131], v[154:157], v[8:11], v[128:131]
	ds_read_b128 v[20:23], v210 offset:24576
	s_waitcnt lgkmcnt(7)
	v_mfma_f32_16x16x32_bf16 v[132:135], v[158:161], v[8:11], v[132:135]
	ds_read_b128 v[28:31], v210 offset:26624
	s_waitcnt lgkmcnt(7)
	v_mfma_f32_16x16x32_bf16 v[178:181], v[162:165], v[8:11], v[178:181]
	ds_read_b128 v[36:39], v210 offset:28672
	s_waitcnt lgkmcnt(7)
	v_mfma_f32_16x16x32_bf16 v[182:185], v[166:169], v[8:11], v[182:185]
	ds_read_b128 v[44:47], v210 offset:30720
	s_waitcnt lgkmcnt(7)
	v_mfma_f32_16x16x32_bf16 v[128:131], v[170:173], v[16:19], v[128:131]
	ds_read_b128 v[52:55], v210 offset:32768
	s_waitcnt lgkmcnt(7)
	v_mfma_f32_16x16x32_bf16 v[132:135], v[174:177], v[16:19], v[132:135]
	ds_read_b128 v[60:63], v210 offset:34816
	s_waitcnt lgkmcnt(7)
	v_mfma_f32_16x16x32_bf16 v[178:181], v[4:7], v[16:19], v[178:181]
	ds_read_b128 v[68:71], v210 offset:36864
	s_waitcnt lgkmcnt(7)
	v_mfma_f32_16x16x32_bf16 v[182:185], v[12:15], v[16:19], v[182:185]
	ds_read_b128 v[76:79], v210 offset:38912
	s_waitcnt lgkmcnt(7)
	v_mfma_f32_16x16x32_bf16 v[128:131], v[20:23], v[24:27], v[128:131]
	ds_read_b128 v[84:87], v210 offset:40960
	s_waitcnt lgkmcnt(7)
	v_mfma_f32_16x16x32_bf16 v[132:135], v[28:31], v[24:27], v[132:135]
	ds_read_b128 v[92:95], v210 offset:43008
	s_waitcnt lgkmcnt(7)
	v_mfma_f32_16x16x32_bf16 v[178:181], v[36:39], v[24:27], v[178:181]
	ds_read_b128 v[100:103], v210 offset:45056
	s_waitcnt lgkmcnt(7)
	v_mfma_f32_16x16x32_bf16 v[182:185], v[44:47], v[24:27], v[182:185]
	ds_read_b128 v[108:111], v210 offset:47104
	s_waitcnt lgkmcnt(7)
	v_mfma_f32_16x16x32_bf16 v[128:131], v[52:55], v[32:35], v[128:131]
	ds_read_b128 v[116:119], v210 offset:49152
	s_waitcnt lgkmcnt(7)
	v_mfma_f32_16x16x32_bf16 v[132:135], v[60:63], v[32:35], v[132:135]
	ds_read_b128 v[124:127], v210 offset:51200
	s_waitcnt lgkmcnt(7)
	v_mfma_f32_16x16x32_bf16 v[178:181], v[68:71], v[32:35], v[178:181]
	ds_read_b128 v[138:141], v210 offset:53248
	s_waitcnt lgkmcnt(7)
	v_mfma_f32_16x16x32_bf16 v[182:185], v[76:79], v[32:35], v[182:185]
	ds_read_b128 v[142:145], v210 offset:55296
	s_waitcnt lgkmcnt(7)
	v_mfma_f32_16x16x32_bf16 v[128:131], v[84:87], v[40:43], v[128:131]
	ds_read_b128 v[146:149], v210 offset:57344
	s_waitcnt lgkmcnt(7)
	v_mfma_f32_16x16x32_bf16 v[132:135], v[92:95], v[40:43], v[132:135]
	ds_read_b128 v[150:153], v210 offset:59392
	s_waitcnt lgkmcnt(7)
	v_mfma_f32_16x16x32_bf16 v[178:181], v[100:103], v[40:43], v[178:181]
	ds_read_b128 v[154:157], v210 offset:61440
	s_waitcnt lgkmcnt(7)
	v_mfma_f32_16x16x32_bf16 v[182:185], v[108:111], v[40:43], v[182:185]
	ds_read_b128 v[158:161], v210 offset:63488
	s_waitcnt lgkmcnt(7)
	v_mfma_f32_16x16x32_bf16 v[128:131], v[116:119], v[48:51], v[128:131]
	ds_read_b128 v[162:165], v211 offset:32768
	s_waitcnt lgkmcnt(7)
	v_mfma_f32_16x16x32_bf16 v[132:135], v[124:127], v[48:51], v[132:135]
	ds_read_b128 v[166:169], v211 offset:33792
	s_waitcnt lgkmcnt(7)
	v_mfma_f32_16x16x32_bf16 v[178:181], v[138:141], v[48:51], v[178:181]
	ds_read_b128 v[170:173], v211 offset:34816
	s_waitcnt lgkmcnt(7)
	v_mfma_f32_16x16x32_bf16 v[182:185], v[142:145], v[48:51], v[182:185]
	ds_read_b128 v[174:177], v211 offset:35840
	s_waitcnt lgkmcnt(7)
	v_mfma_f32_16x16x32_bf16 v[128:131], v[146:149], v[56:59], v[128:131]
	ds_read_b128 v[4:7], v211 offset:36864
	s_waitcnt lgkmcnt(7)
	v_mfma_f32_16x16x32_bf16 v[132:135], v[150:153], v[56:59], v[132:135]
	ds_read_b128 v[12:15], v211 offset:37888
	s_waitcnt lgkmcnt(7)
	v_mfma_f32_16x16x32_bf16 v[178:181], v[154:157], v[56:59], v[178:181]
	ds_read_b128 v[20:23], v211 offset:38912
	s_waitcnt lgkmcnt(7)
	v_mfma_f32_16x16x32_bf16 v[182:185], v[158:161], v[56:59], v[182:185]
	ds_read_b128 v[28:31], v211 offset:39936
	s_waitcnt lgkmcnt(7)
	v_mfma_f32_16x16x32_bf16 v[128:131], v[162:165], v[64:67], v[128:131]
	ds_read_b128 v[36:39], v211 offset:40960
	s_waitcnt lgkmcnt(7)
	v_mfma_f32_16x16x32_bf16 v[132:135], v[166:169], v[64:67], v[132:135]
	ds_read_b128 v[44:47], v211 offset:41984
	s_waitcnt lgkmcnt(7)
	v_mfma_f32_16x16x32_bf16 v[178:181], v[170:173], v[64:67], v[178:181]
	ds_read_b128 v[52:55], v211 offset:43008
	s_waitcnt lgkmcnt(7)
	v_mfma_f32_16x16x32_bf16 v[182:185], v[174:177], v[64:67], v[182:185]
	ds_read_b128 v[60:63], v211 offset:44032
	s_waitcnt lgkmcnt(7)
	v_mfma_f32_16x16x32_bf16 v[128:131], v[4:7], v[72:75], v[128:131]
	ds_read_b128 v[68:71], v211 offset:45056
	s_waitcnt lgkmcnt(7)
	v_mfma_f32_16x16x32_bf16 v[132:135], v[12:15], v[72:75], v[132:135]
	ds_read_b128 v[76:79], v211 offset:46080
	s_waitcnt lgkmcnt(7)
	v_mfma_f32_16x16x32_bf16 v[178:181], v[20:23], v[72:75], v[178:181]
	ds_read_b128 v[84:87], v211 offset:47104
	s_waitcnt lgkmcnt(7)
	v_mfma_f32_16x16x32_bf16 v[182:185], v[28:31], v[72:75], v[182:185]
	ds_read_b128 v[92:95], v211 offset:48128
	s_waitcnt lgkmcnt(7)
	v_mfma_f32_16x16x32_bf16 v[128:131], v[36:39], v[80:83], v[128:131]
	ds_read_b128 v[100:103], v211 offset:49152
	s_waitcnt lgkmcnt(7)
	v_mfma_f32_16x16x32_bf16 v[132:135], v[44:47], v[80:83], v[132:135]
	ds_read_b128 v[108:111], v211 offset:50176
	s_waitcnt lgkmcnt(7)
	v_mfma_f32_16x16x32_bf16 v[178:181], v[52:55], v[80:83], v[178:181]
	ds_read_b128 v[116:119], v211 offset:51200
	s_waitcnt lgkmcnt(7)
	v_mfma_f32_16x16x32_bf16 v[182:185], v[60:63], v[80:83], v[182:185]
	ds_read_b128 v[124:127], v211 offset:52224
	s_waitcnt lgkmcnt(7)
	v_mfma_f32_16x16x32_bf16 v[128:131], v[68:71], v[88:91], v[128:131]
	ds_read_b128 v[138:141], v211 offset:53248
	s_waitcnt lgkmcnt(7)
	v_mfma_f32_16x16x32_bf16 v[132:135], v[76:79], v[88:91], v[132:135]
	ds_read_b128 v[142:145], v211 offset:54272
	s_waitcnt lgkmcnt(7)
	v_mfma_f32_16x16x32_bf16 v[178:181], v[84:87], v[88:91], v[178:181]
	ds_read_b128 v[146:149], v211 offset:55296
	s_waitcnt lgkmcnt(7)
	v_mfma_f32_16x16x32_bf16 v[182:185], v[92:95], v[88:91], v[182:185]
	ds_read_b128 v[150:153], v211 offset:56320
	s_waitcnt lgkmcnt(7)
	v_mfma_f32_16x16x32_bf16 v[128:131], v[100:103], v[96:99], v[128:131]
	ds_read_b128 v[154:157], v211 offset:57344
	s_waitcnt lgkmcnt(7)
	v_mfma_f32_16x16x32_bf16 v[132:135], v[108:111], v[96:99], v[132:135]
	ds_read_b128 v[158:161], v211 offset:58368
	s_waitcnt lgkmcnt(7)
	v_mfma_f32_16x16x32_bf16 v[178:181], v[116:119], v[96:99], v[178:181]
	ds_read_b128 v[162:165], v211 offset:59392
	s_waitcnt lgkmcnt(7)
	v_mfma_f32_16x16x32_bf16 v[182:185], v[124:127], v[96:99], v[182:185]
	ds_read_b128 v[166:169], v211 offset:60416
	s_waitcnt lgkmcnt(7)
	v_mfma_f32_16x16x32_bf16 v[128:131], v[138:141], v[104:107], v[128:131]
	ds_read_b128 v[170:173], v211 offset:61440
	s_waitcnt lgkmcnt(7)
	v_mfma_f32_16x16x32_bf16 v[132:135], v[142:145], v[104:107], v[132:135]
	ds_read_b128 v[174:177], v211 offset:62464
	s_waitcnt lgkmcnt(7)
	v_mfma_f32_16x16x32_bf16 v[178:181], v[146:149], v[104:107], v[178:181]
	ds_read_b128 v[4:7], v211 offset:63488
	s_waitcnt lgkmcnt(7)
	v_mfma_f32_16x16x32_bf16 v[182:185], v[150:153], v[104:107], v[182:185]
	ds_read_b128 v[12:15], v211 offset:64512
	s_waitcnt lgkmcnt(7)
	v_mfma_f32_16x16x32_bf16 v[128:131], v[154:157], v[112:115], v[128:131]
	s_waitcnt lgkmcnt(6)
	v_mfma_f32_16x16x32_bf16 v[132:135], v[158:161], v[112:115], v[132:135]
	s_waitcnt lgkmcnt(5)
	v_mfma_f32_16x16x32_bf16 v[178:181], v[162:165], v[112:115], v[178:181]
	s_waitcnt lgkmcnt(4)
	v_mfma_f32_16x16x32_bf16 v[182:185], v[166:169], v[112:115], v[182:185]
	s_waitcnt lgkmcnt(3)
	v_mfma_f32_16x16x32_bf16 v[128:131], v[170:173], v[120:123], v[128:131]
	s_waitcnt lgkmcnt(2)
	v_mfma_f32_16x16x32_bf16 v[132:135], v[174:177], v[120:123], v[132:135]
	s_waitcnt lgkmcnt(1)
	v_mfma_f32_16x16x32_bf16 v[178:181], v[4:7], v[120:123], v[178:181]
	s_waitcnt lgkmcnt(0)
	v_mfma_f32_16x16x32_bf16 v[182:185], v[12:15], v[120:123], v[182:185]
	ds_bpermute_b32 v136, v215, v212
	s_waitcnt lgkmcnt(0)
	v_add_f32_e32 v212, v212, v136
	ds_bpermute_b32 v136, v216, v212
	s_waitcnt lgkmcnt(0)
	v_add_f32_e32 v212, v212, v136
	v_rcp_f32_e32 v213, v212
	s_nop 0
	v_fma_f32 v136, -v212, v213, 1.0
	v_fma_f32 v213, v136, v213, v213
	v_mul_u32_u24_e32 v208, 0x600, v206
	v_lshl_add_u32 v208, v207, 3, v208
	s_add_u32 s10, s4, s38
	s_addc_u32 s11, s5, 0
	s_nop 2
	v_mul_f32_e32 v128, v128, v213
	v_mul_f32_e32 v129, v129, v213
	v_mul_f32_e32 v130, v130, v213
	v_mul_f32_e32 v131, v131, v213
	v_cvt_pk_bf16_f32 v128, v128, v129
	v_cvt_pk_bf16_f32 v129, v130, v131
	global_store_dwordx2 v208, v[128:129], s[10:11] offset:0
	v_mul_f32_e32 v132, v132, v213
	v_mul_f32_e32 v133, v133, v213
	v_mul_f32_e32 v134, v134, v213
	v_mul_f32_e32 v135, v135, v213
	v_cvt_pk_bf16_f32 v132, v132, v133
	v_cvt_pk_bf16_f32 v133, v134, v135
	global_store_dwordx2 v208, v[132:133], s[10:11] offset:32
	v_mul_f32_e32 v178, v178, v213
	v_mul_f32_e32 v179, v179, v213
	v_mul_f32_e32 v180, v180, v213
	v_mul_f32_e32 v181, v181, v213
	v_cvt_pk_bf16_f32 v178, v178, v179
	v_cvt_pk_bf16_f32 v179, v180, v181
	global_store_dwordx2 v208, v[178:179], s[10:11] offset:64
	v_mul_f32_e32 v182, v182, v213
	v_mul_f32_e32 v183, v183, v213
	v_mul_f32_e32 v184, v184, v213
	v_mul_f32_e32 v185, v185, v213
	v_cvt_pk_bf16_f32 v182, v182, v183
	v_cvt_pk_bf16_f32 v183, v184, v185
	global_store_dwordx2 v208, v[182:183], s[10:11] offset:96
